# GEMM MFMA segments: removed duplicate lgkmcnt(0) behind each barrier and the mid-segment setprio toggle (32 MFMAs now issue back to back)
# baseline (speedup 1.0000x reference)
; #define PG8_STAGE(bufoff, gbase, voff) do { _Pragma("unroll") for (int _i = 0; _i < 2; ++_i) \
;         __builtin_amdgcn_global_load_lds((const unsigned*)((const char*)(gbase) + (voff)[_i]), (PG8_LAS unsigned*)(lds + (bufoff) + ldsw + _i * 8192), 16, 0, 0); } while (0)
; #define PG8_LDA(dst, b, h) do { _Pragma("unroll") for (int m = 0; m < 4; ++m) _Pragma("unroll") for (int k = 0; k < 2; ++k) dst[m][k] = *(const PG8_LAS bf16x8*)(lds + PG8_SA(b, h) + aoff + m * 2048 + k * 1024); } while (0)
; #define PG8_LDB(dst, b, h) do { _Pragma("unroll") for (int n = 0; n < 2; ++n) _Pragma("unroll") for (int k = 0; k < 2; ++k) dst[n][k] = *(const PG8_LAS bf16x8*)(lds + PG8_SB(b, h) + boff + n * 2048 + k * 1024); } while (0)
; #define PG8_MMA(ai, bj, At, Bt) do { __builtin_amdgcn_s_setprio(1); _Pragma("unroll") for (int m = 0; m < 4; ++m) _Pragma("unroll") for (int n = 0; n < 2; ++n) _Pragma("unroll") for (int k = 0; k < 2; ++k) \
;         acc[ai][bj][m][n] = __builtin_amdgcn_mfma_f32_16x16x32_bf16(Bt[n][k], At[m][k], acc[ai][bj][m][n], 0, 0, 0); __builtin_amdgcn_s_setprio(0); } while (0)
; #define PG8_WAIT_V(n) asm volatile("s_waitcnt vmcnt(" #n ")" ::: "memory")
; #define PG8_WAIT_L(n) asm volatile("s_waitcnt lgkmcnt(" #n ")" ::: "memory")
; #define PG8_BAR __builtin_amdgcn_s_barrier()
; #define PG8_SCHED __builtin_amdgcn_sched_barrier(0)
; template <class Epi, class Sched, bool ALIGN_EPI = false, bool SP2 = false>
; __device__ __forceinline__ void gemm_phase(PG8_LAS unsigned char* lds, const Gemm g, const Sched& S, const Epi& E, const int tid_in) {
;     ...
;             PG8_LDB(B0, 0, 0); PG8_LDB(B1, 0, 1); PG8_SCHED; PG8_LDA(At, 0, 0); PG8_STAGE(PG8_SA(1, 1), a1 + hstep, voffA);
;             PG8_WAIT_V(8); PG8_WAIT_L(0); PG8_BAR; PG8_MMA(0, 0, At, B0); PG8_MMA(0, 1, At, B1); PG8_BAR; PG8_SCHED;
;             PG8_LDA(At, 0, 1); PG8_STAGE(PG8_SB(0, 0), b2, voffB); PG8_STAGE(PG8_SB(0, 1), b2 + hstep, voffB); PG8_STAGE(PG8_SA(0, 0), a2, voffA);
;             PG8_WAIT_V(8); PG8_WAIT_L(0); PG8_BAR; PG8_MMA(1, 0, At, B0); PG8_MMA(1, 1, At, B1); PG8_BAR; PG8_SCHED;
.LBB0_115:
	s_add_i32 s77, s52, 2
	s_add_u32 vcc_lo, s2, s10
	s_addc_u32 s53, s3, s11
	s_add_u32 s44, s50, s10
	s_addc_u32 s45, s51, s11
	s_add_i32 s16, 0, 0x10000
	s_cmp_eq_u32 s68, s52
	s_cselect_b32 s53, s49, s53
	s_cselect_b32 s52, s48, vcc_lo
	s_cselect_b32 vcc_hi, s43, s45
	s_cselect_b32 vcc_lo, s42, s44
	s_add_i32 s17, 0, 0x14000
	ds_read_b128 v[134:137], v248
	ds_read_b128 v[138:141], v248 offset:1024
	ds_read_b128 v[142:145], v248 offset:2048
	ds_read_b128 v[146:149], v248 offset:3072
	ds_read_b128 v[150:153], v249
	ds_read_b128 v[154:157], v249 offset:1024
	ds_read_b128 v[158:161], v249 offset:2048
	ds_read_b128 v[180:183], v249 offset:3072
	s_add_i32 m0, s60, 0xc000
	ds_read_b128 v[184:187], v179
	ds_read_b128 v[188:191], v179 offset:1024
	ds_read_b128 v[192:195], v179 offset:2048
	ds_read_b128 v[196:199], v179 offset:3072
	ds_read_b128 v[200:203], v179 offset:4096
	ds_read_b128 v[204:207], v179 offset:5120
	ds_read_b128 v[208:211], v179 offset:6144
	ds_read_b128 v[212:215], v179 offset:7168
	global_load_lds_dwordx4 v132, s[2:3]
	s_add_i32 m0, s60, 0xe000
	s_nop 0
	global_load_lds_dwordx4 v130, s[2:3]
	s_waitcnt vmcnt(8)
	s_waitcnt lgkmcnt(0)
	s_barrier
	s_setprio 1
	v_mfma_f32_16x16x32_bf16 v[126:129], v[134:137], v[184:187], v[126:129]
	v_mfma_f32_16x16x32_bf16 v[122:125], v[142:145], v[184:187], v[122:125]
	v_mfma_f32_16x16x32_bf16 v[110:113], v[134:137], v[192:195], v[110:113]
	v_mfma_f32_16x16x32_bf16 v[106:109], v[142:145], v[192:195], v[106:109]
	v_mfma_f32_16x16x32_bf16 v[94:97], v[134:137], v[200:203], v[94:97]
	v_mfma_f32_16x16x32_bf16 v[90:93], v[142:145], v[200:203], v[90:93]
	v_mfma_f32_16x16x32_bf16 v[78:81], v[134:137], v[208:211], v[78:81]
	v_mfma_f32_16x16x32_bf16 v[74:77], v[142:145], v[208:211], v[74:77]
	v_mfma_f32_16x16x32_bf16 v[126:129], v[138:141], v[188:191], v[126:129]
	v_mfma_f32_16x16x32_bf16 v[122:125], v[146:149], v[188:191], v[122:125]
	v_mfma_f32_16x16x32_bf16 v[110:113], v[138:141], v[196:199], v[110:113]
	v_mfma_f32_16x16x32_bf16 v[106:109], v[146:149], v[196:199], v[106:109]
	v_mfma_f32_16x16x32_bf16 v[94:97], v[138:141], v[204:207], v[94:97]
	v_mfma_f32_16x16x32_bf16 v[90:93], v[146:149], v[204:207], v[90:93]
	v_mfma_f32_16x16x32_bf16 v[78:81], v[138:141], v[212:215], v[78:81]
	v_mfma_f32_16x16x32_bf16 v[74:77], v[146:149], v[212:215], v[74:77]
	v_mfma_f32_16x16x32_bf16 v[118:121], v[150:153], v[184:187], v[118:121]
	v_mfma_f32_16x16x32_bf16 v[114:117], v[158:161], v[184:187], v[114:117]
	v_mfma_f32_16x16x32_bf16 v[102:105], v[150:153], v[192:195], v[102:105]
	v_mfma_f32_16x16x32_bf16 v[98:101], v[158:161], v[192:195], v[98:101]
	v_mfma_f32_16x16x32_bf16 v[86:89], v[150:153], v[200:203], v[86:89]
	v_mfma_f32_16x16x32_bf16 v[82:85], v[158:161], v[200:203], v[82:85]
	v_mfma_f32_16x16x32_bf16 v[70:73], v[150:153], v[208:211], v[70:73]
	v_mfma_f32_16x16x32_bf16 v[66:69], v[158:161], v[208:211], v[66:69]
	v_mfma_f32_16x16x32_bf16 v[118:121], v[154:157], v[188:191], v[118:121]
	v_mfma_f32_16x16x32_bf16 v[114:117], v[180:183], v[188:191], v[114:117]
	v_mfma_f32_16x16x32_bf16 v[102:105], v[154:157], v[196:199], v[102:105]
	v_mfma_f32_16x16x32_bf16 v[98:101], v[180:183], v[196:199], v[98:101]
	v_mfma_f32_16x16x32_bf16 v[86:89], v[154:157], v[204:207], v[86:89]
	v_mfma_f32_16x16x32_bf16 v[82:85], v[180:183], v[204:207], v[82:85]
	v_mfma_f32_16x16x32_bf16 v[70:73], v[154:157], v[212:215], v[70:73]
	v_mfma_f32_16x16x32_bf16 v[66:69], v[180:183], v[212:215], v[66:69]
	s_setprio 0
	s_barrier
	s_add_i32 s16, s16, s59
	s_add_u32 s98, vcc_lo, 0x80
	s_addc_u32 s99, vcc_hi, 0
	s_add_u32 s100, s52, 0x80
	s_addc_u32 s101, s53, 0
	s_mov_b32 m0, s16
	ds_read_b128 v[184:187], v179 offset:16384
	ds_read_b128 v[188:191], v179 offset:17408
	ds_read_b128 v[192:195], v179 offset:18432
	ds_read_b128 v[196:199], v179 offset:19456
	ds_read_b128 v[200:203], v179 offset:20480
	ds_read_b128 v[204:207], v179 offset:21504
	ds_read_b128 v[208:211], v179 offset:22528
	ds_read_b128 v[212:215], v179 offset:23552
	global_load_lds_dwordx4 v164, vcc
	s_add_i32 m0, s16, 0x2000
	s_add_i32 s16, s17, s59
	global_load_lds_dwordx4 v168, vcc
	s_add_u32 vcc_lo, vcc_lo, s82
	s_addc_u32 vcc_hi, vcc_hi, 0
	s_mov_b32 m0, s16
	s_nop 0
	global_load_lds_dwordx4 v164, vcc
	s_add_i32 m0, s16, 0x2000
	s_nop 0
	global_load_lds_dwordx4 v168, vcc
	s_mov_b32 m0, s60
	s_nop 0
	global_load_lds_dwordx4 v162, s[52:53]
	s_mov_b32 m0, s61
	s_nop 0
	global_load_lds_dwordx4 v166, s[52:53]
	s_waitcnt vmcnt(8)
	s_waitcnt lgkmcnt(0)
	s_barrier
	s_setprio 1
	v_mfma_f32_16x16x32_bf16 v[62:65], v[134:137], v[184:187], v[62:65]
	v_mfma_f32_16x16x32_bf16 v[58:61], v[142:145], v[184:187], v[58:61]
	v_mfma_f32_16x16x32_bf16 v[46:49], v[134:137], v[192:195], v[46:49]
	v_mfma_f32_16x16x32_bf16 v[42:45], v[142:145], v[192:195], v[42:45]
	v_mfma_f32_16x16x32_bf16 v[30:33], v[134:137], v[200:203], v[30:33]
	v_mfma_f32_16x16x32_bf16 v[26:29], v[142:145], v[200:203], v[26:29]
	v_mfma_f32_16x16x32_bf16 v[14:17], v[134:137], v[208:211], v[14:17]
	v_mfma_f32_16x16x32_bf16 v[10:13], v[142:145], v[208:211], v[10:13]
	v_mfma_f32_16x16x32_bf16 v[62:65], v[138:141], v[188:191], v[62:65]
	v_mfma_f32_16x16x32_bf16 v[58:61], v[146:149], v[188:191], v[58:61]
	v_mfma_f32_16x16x32_bf16 v[46:49], v[138:141], v[196:199], v[46:49]
	v_mfma_f32_16x16x32_bf16 v[42:45], v[146:149], v[196:199], v[42:45]
	v_mfma_f32_16x16x32_bf16 v[30:33], v[138:141], v[204:207], v[30:33]
	v_mfma_f32_16x16x32_bf16 v[26:29], v[146:149], v[204:207], v[26:29]
	v_mfma_f32_16x16x32_bf16 v[14:17], v[138:141], v[212:215], v[14:17]
	v_mfma_f32_16x16x32_bf16 v[10:13], v[146:149], v[212:215], v[10:13]
	v_mfma_f32_16x16x32_bf16 v[54:57], v[150:153], v[184:187], v[54:57]
	v_mfma_f32_16x16x32_bf16 v[50:53], v[158:161], v[184:187], v[50:53]
	v_mfma_f32_16x16x32_bf16 v[38:41], v[150:153], v[192:195], v[38:41]
	v_mfma_f32_16x16x32_bf16 v[34:37], v[158:161], v[192:195], v[34:37]
	v_mfma_f32_16x16x32_bf16 v[22:25], v[150:153], v[200:203], v[22:25]
	v_mfma_f32_16x16x32_bf16 v[18:21], v[158:161], v[200:203], v[18:21]
	v_mfma_f32_16x16x32_bf16 v[6:9], v[150:153], v[208:211], v[6:9]
	v_mfma_f32_16x16x32_bf16 v[2:5], v[158:161], v[208:211], v[2:5]
	v_mfma_f32_16x16x32_bf16 v[54:57], v[154:157], v[188:191], v[54:57]
	v_mfma_f32_16x16x32_bf16 v[50:53], v[180:183], v[188:191], v[50:53]
	v_mfma_f32_16x16x32_bf16 v[38:41], v[154:157], v[196:199], v[38:41]
	v_mfma_f32_16x16x32_bf16 v[34:37], v[180:183], v[196:199], v[34:37]
	v_mfma_f32_16x16x32_bf16 v[22:25], v[154:157], v[204:207], v[22:25]
	v_mfma_f32_16x16x32_bf16 v[18:21], v[180:183], v[204:207], v[18:21]
	v_mfma_f32_16x16x32_bf16 v[6:9], v[154:157], v[212:215], v[6:9]
	v_mfma_f32_16x16x32_bf16 v[2:5], v[180:183], v[212:215], v[2:5]
	s_setprio 0
	s_barrier
; #define PG8_STAGE(bufoff, gbase, voff) do { _Pragma("unroll") for (int _i = 0; _i < 2; ++_i) \
;         __builtin_amdgcn_global_load_lds((const unsigned*)((const char*)(gbase) + (voff)[_i]), (PG8_LAS unsigned*)(lds + (bufoff) + ldsw + _i * 8192), 16, 0, 0); } while (0)
; #define PG8_LDA(dst, b, h) do { _Pragma("unroll") for (int m = 0; m < 4; ++m) _Pragma("unroll") for (int k = 0; k < 2; ++k) dst[m][k] = *(const PG8_LAS bf16x8*)(lds + PG8_SA(b, h) + aoff + m * 2048 + k * 1024); } while (0)
; #define PG8_LDB(dst, b, h) do { _Pragma("unroll") for (int n = 0; n < 2; ++n) _Pragma("unroll") for (int k = 0; k < 2; ++k) dst[n][k] = *(const PG8_LAS bf16x8*)(lds + PG8_SB(b, h) + boff + n * 2048 + k * 1024); } while (0)
; #define PG8_MMA(ai, bj, At, Bt) do { __builtin_amdgcn_s_setprio(1); _Pragma("unroll") for (int m = 0; m < 4; ++m) _Pragma("unroll") for (int n = 0; n < 2; ++n) _Pragma("unroll") for (int k = 0; k < 2; ++k) \
;         acc[ai][bj][m][n] = __builtin_amdgcn_mfma_f32_16x16x32_bf16(Bt[n][k], At[m][k], acc[ai][bj][m][n], 0, 0, 0); __builtin_amdgcn_s_setprio(0); } while (0)
; #define PG8_WAIT_V(n) asm volatile("s_waitcnt vmcnt(" #n ")" ::: "memory")
; #define PG8_WAIT_L(n) asm volatile("s_waitcnt lgkmcnt(" #n ")" ::: "memory")
; #define PG8_BAR __builtin_amdgcn_s_barrier()
; #define PG8_SCHED __builtin_amdgcn_sched_barrier(0)
; template <class Epi, class Sched, bool ALIGN_EPI = false, bool SP2 = false>
; __device__ __forceinline__ void gemm_phase(PG8_LAS unsigned char* lds, const Gemm g, const Sched& S, const Epi& E, const int tid_in) {
;     ...
;             PG8_LDB(B0, 1, 0); PG8_LDB(B1, 1, 1); PG8_SCHED; PG8_LDA(At, 1, 0); PG8_STAGE(PG8_SA(0, 1), a2 + hstep, voffA);
;             PG8_WAIT_V(8); PG8_WAIT_L(0); PG8_BAR; PG8_MMA(0, 0, At, B0); PG8_MMA(0, 1, At, B1); PG8_BAR; PG8_SCHED;
;             PG8_LDA(At, 1, 1); PG8_STAGE(PG8_SB(1, 0), b3, voffB); PG8_STAGE(PG8_SB(1, 1), b3 + hstep, voffB); PG8_STAGE(PG8_SA(1, 0), a3, voffA);
;             PG8_WAIT_V(8); PG8_WAIT_L(0); PG8_BAR; PG8_MMA(1, 0, At, B0); PG8_MMA(1, 1, At, B1); PG8_BAR; PG8_SCHED;
	s_add_i32 s16, 0, 0x18000
	s_add_i32 s17, 0, 0x1c000
	ds_read_b128 v[134:137], v250
	ds_read_b128 v[138:141], v250 offset:1024
	ds_read_b128 v[142:145], v250 offset:2048
	ds_read_b128 v[146:149], v250 offset:3072
	ds_read_b128 v[150:153], v251
	ds_read_b128 v[154:157], v251 offset:1024
	ds_read_b128 v[158:161], v251 offset:2048
	ds_read_b128 v[180:183], v251 offset:3072
	s_add_u32 s52, s52, s82
	s_addc_u32 s53, s53, 0
	s_mov_b32 m0, s62
	ds_read_b128 v[184:187], v179 offset:32768
	ds_read_b128 v[188:191], v179 offset:33792
	ds_read_b128 v[192:195], v179 offset:34816
	ds_read_b128 v[196:199], v179 offset:35840
	ds_read_b128 v[200:203], v179 offset:36864
	ds_read_b128 v[204:207], v179 offset:37888
	ds_read_b128 v[208:211], v179 offset:38912
	ds_read_b128 v[212:215], v179 offset:39936
	global_load_lds_dwordx4 v162, s[52:53]
	s_mov_b32 m0, s63
	s_nop 0
	global_load_lds_dwordx4 v166, s[52:53]
	s_waitcnt vmcnt(8)
	s_waitcnt lgkmcnt(0)
	s_barrier
	s_setprio 1
	v_mfma_f32_16x16x32_bf16 v[126:129], v[134:137], v[184:187], v[126:129]
	v_mfma_f32_16x16x32_bf16 v[122:125], v[142:145], v[184:187], v[122:125]
	v_mfma_f32_16x16x32_bf16 v[110:113], v[134:137], v[192:195], v[110:113]
	v_mfma_f32_16x16x32_bf16 v[106:109], v[142:145], v[192:195], v[106:109]
	v_mfma_f32_16x16x32_bf16 v[94:97], v[134:137], v[200:203], v[94:97]
	v_mfma_f32_16x16x32_bf16 v[90:93], v[142:145], v[200:203], v[90:93]
	v_mfma_f32_16x16x32_bf16 v[78:81], v[134:137], v[208:211], v[78:81]
	v_mfma_f32_16x16x32_bf16 v[74:77], v[142:145], v[208:211], v[74:77]
	v_mfma_f32_16x16x32_bf16 v[126:129], v[138:141], v[188:191], v[126:129]
	v_mfma_f32_16x16x32_bf16 v[122:125], v[146:149], v[188:191], v[122:125]
	v_mfma_f32_16x16x32_bf16 v[110:113], v[138:141], v[196:199], v[110:113]
	v_mfma_f32_16x16x32_bf16 v[106:109], v[146:149], v[196:199], v[106:109]
	v_mfma_f32_16x16x32_bf16 v[94:97], v[138:141], v[204:207], v[94:97]
	v_mfma_f32_16x16x32_bf16 v[90:93], v[146:149], v[204:207], v[90:93]
	v_mfma_f32_16x16x32_bf16 v[78:81], v[138:141], v[212:215], v[78:81]
	v_mfma_f32_16x16x32_bf16 v[74:77], v[146:149], v[212:215], v[74:77]
	v_mfma_f32_16x16x32_bf16 v[118:121], v[150:153], v[184:187], v[118:121]
	v_mfma_f32_16x16x32_bf16 v[114:117], v[158:161], v[184:187], v[114:117]
	v_mfma_f32_16x16x32_bf16 v[102:105], v[150:153], v[192:195], v[102:105]
	v_mfma_f32_16x16x32_bf16 v[98:101], v[158:161], v[192:195], v[98:101]
	v_mfma_f32_16x16x32_bf16 v[86:89], v[150:153], v[200:203], v[86:89]
	v_mfma_f32_16x16x32_bf16 v[82:85], v[158:161], v[200:203], v[82:85]
	v_mfma_f32_16x16x32_bf16 v[70:73], v[150:153], v[208:211], v[70:73]
	v_mfma_f32_16x16x32_bf16 v[66:69], v[158:161], v[208:211], v[66:69]
	v_mfma_f32_16x16x32_bf16 v[118:121], v[154:157], v[188:191], v[118:121]
	v_mfma_f32_16x16x32_bf16 v[114:117], v[180:183], v[188:191], v[114:117]
	v_mfma_f32_16x16x32_bf16 v[102:105], v[154:157], v[196:199], v[102:105]
	v_mfma_f32_16x16x32_bf16 v[98:101], v[180:183], v[196:199], v[98:101]
	v_mfma_f32_16x16x32_bf16 v[86:89], v[154:157], v[204:207], v[86:89]
	v_mfma_f32_16x16x32_bf16 v[82:85], v[180:183], v[204:207], v[82:85]
	v_mfma_f32_16x16x32_bf16 v[70:73], v[154:157], v[212:215], v[70:73]
	v_mfma_f32_16x16x32_bf16 v[66:69], v[180:183], v[212:215], v[66:69]
	s_setprio 0
	s_barrier
	s_add_i32 s16, s16, s59
	s_mov_b32 m0, s16
	ds_read_b128 v[184:187], v179 offset:49152
	ds_read_b128 v[188:191], v179 offset:50176
	ds_read_b128 v[192:195], v179 offset:51200
	ds_read_b128 v[196:199], v179 offset:52224
	ds_read_b128 v[200:203], v179 offset:53248
	ds_read_b128 v[204:207], v179 offset:54272
	ds_read_b128 v[208:211], v179 offset:55296
	ds_read_b128 v[212:215], v179 offset:56320
	global_load_lds_dwordx4 v164, s[98:99]
	s_add_i32 m0, s16, 0x2000
	s_add_i32 s16, s17, s59
	global_load_lds_dwordx4 v168, s[98:99]
	s_add_u32 vcc_lo, vcc_lo, 0x80
	s_addc_u32 vcc_hi, vcc_hi, 0
	s_mov_b32 m0, s16
	s_nop 0
	global_load_lds_dwordx4 v164, vcc
	s_add_i32 m0, s16, 0x2000
	s_nop 0
	global_load_lds_dwordx4 v168, vcc
	s_mov_b32 m0, s66
	s_nop 0
	global_load_lds_dwordx4 v162, s[100:101]
	s_mov_b32 m0, s67
	s_nop 0
	global_load_lds_dwordx4 v166, s[100:101]
	s_waitcnt vmcnt(8)
	s_waitcnt lgkmcnt(0)
	s_barrier
	s_setprio 1
	v_mfma_f32_16x16x32_bf16 v[62:65], v[134:137], v[184:187], v[62:65]
	v_mfma_f32_16x16x32_bf16 v[58:61], v[142:145], v[184:187], v[58:61]
	v_mfma_f32_16x16x32_bf16 v[46:49], v[134:137], v[192:195], v[46:49]
	v_mfma_f32_16x16x32_bf16 v[42:45], v[142:145], v[192:195], v[42:45]
	v_mfma_f32_16x16x32_bf16 v[30:33], v[134:137], v[200:203], v[30:33]
	v_mfma_f32_16x16x32_bf16 v[26:29], v[142:145], v[200:203], v[26:29]
	v_mfma_f32_16x16x32_bf16 v[14:17], v[134:137], v[208:211], v[14:17]
	v_mfma_f32_16x16x32_bf16 v[10:13], v[142:145], v[208:211], v[10:13]
	v_mfma_f32_16x16x32_bf16 v[62:65], v[138:141], v[188:191], v[62:65]
	v_mfma_f32_16x16x32_bf16 v[58:61], v[146:149], v[188:191], v[58:61]
	v_mfma_f32_16x16x32_bf16 v[46:49], v[138:141], v[196:199], v[46:49]
	v_mfma_f32_16x16x32_bf16 v[42:45], v[146:149], v[196:199], v[42:45]
	v_mfma_f32_16x16x32_bf16 v[30:33], v[138:141], v[204:207], v[30:33]
	v_mfma_f32_16x16x32_bf16 v[26:29], v[146:149], v[204:207], v[26:29]
	v_mfma_f32_16x16x32_bf16 v[14:17], v[138:141], v[212:215], v[14:17]
	v_mfma_f32_16x16x32_bf16 v[10:13], v[146:149], v[212:215], v[10:13]
	v_mfma_f32_16x16x32_bf16 v[54:57], v[150:153], v[184:187], v[54:57]
	v_mfma_f32_16x16x32_bf16 v[50:53], v[158:161], v[184:187], v[50:53]
	v_mfma_f32_16x16x32_bf16 v[38:41], v[150:153], v[192:195], v[38:41]
	v_mfma_f32_16x16x32_bf16 v[34:37], v[158:161], v[192:195], v[34:37]
	v_mfma_f32_16x16x32_bf16 v[22:25], v[150:153], v[200:203], v[22:25]
	v_mfma_f32_16x16x32_bf16 v[18:21], v[158:161], v[200:203], v[18:21]
	v_mfma_f32_16x16x32_bf16 v[6:9], v[150:153], v[208:211], v[6:9]
	v_mfma_f32_16x16x32_bf16 v[2:5], v[158:161], v[208:211], v[2:5]
	v_mfma_f32_16x16x32_bf16 v[54:57], v[154:157], v[188:191], v[54:57]
	v_mfma_f32_16x16x32_bf16 v[50:53], v[180:183], v[188:191], v[50:53]
	v_mfma_f32_16x16x32_bf16 v[38:41], v[154:157], v[196:199], v[38:41]
	v_mfma_f32_16x16x32_bf16 v[34:37], v[180:183], v[196:199], v[34:37]
	v_mfma_f32_16x16x32_bf16 v[22:25], v[154:157], v[204:207], v[22:25]
	v_mfma_f32_16x16x32_bf16 v[18:21], v[180:183], v[204:207], v[18:21]
	v_mfma_f32_16x16x32_bf16 v[6:9], v[154:157], v[212:215], v[6:9]
	v_mfma_f32_16x16x32_bf16 v[2:5], v[180:183], v[212:215], v[2:5]
	s_setprio 0
	s_barrier
	s_add_u32 s10, s10, 0x100
	s_addc_u32 s11, s11, 0
	v_lshl_add_u64 v[132:133], v[132:133], 0, s[88:89]
	v_lshl_add_u64 v[130:131], v[130:131], 0, s[88:89]
	s_cmp_ge_u32 s77, s65
	s_mov_b32 s52, s77
	s_cbranch_scc0 .LBB0_115
	s_and_b64 vcc, exec, s[46:47]
	s_cbranch_vccz .LBB0_118
	s_barrier
